# up-projection (P7) fp8 GEMM k-loop only: one workgroup barrier per phase instead of two (waves 0-3 pre-MMA barrier, waves 4-7 post-MMA barrier)
# baseline (speedup 1.0000x reference)
.LBB0_733:
	s_add_u32 s6, s74, 0xbc00000
	s_addc_u32 s7, s75, 0
	s_and_b32 s12, s8, 3
	s_mov_b64 s[8:9], 0x80
	s_add_i32 m0, s21, 0x18000
	v_lshl_add_u64 v[8:9], v[8:9], 0, s[8:9]
	s_lshl_b32 s13, s3, 13
	s_lshl_b32 s14, s12, 12
	s_waitcnt vmcnt(2)
	v_readfirstlane_b32 s98, v0
	s_nop 3
	s_lshr_b32 s98, s98, 8
	s_barrier
	global_load_lds_dwordx4 v[8:9], off
	v_lshl_add_u64 v[6:7], v[6:7], 0, s[8:9]
	s_add_i32 m0, s21, 0x1a000
	s_add_i32 s43, s21, 0x8000
	s_add_i32 s44, s21, 0xa000
	global_load_lds_dwordx4 v[6:7], off
	v_lshl_add_u64 v[2:3], v[2:3], 0, s[8:9]
	s_mov_b32 m0, s43
	s_add_u32 s10, s24, 0x4080
	global_load_lds_dwordx4 v[2:3], off
	v_lshl_add_u64 v[2:3], v[4:5], 0, s[8:9]
	s_mov_b32 m0, s44
	s_addc_u32 s11, s25, 0
	global_load_lds_dwordx4 v[2:3], off
	s_add_i32 m0, s21, 0x1c000
	v_lshl_add_u64 v[2:3], s[10:11], 0, v[160:161]
	global_load_lds_dwordx4 v[2:3], off
	v_lshl_add_u64 v[2:3], s[10:11], 0, v[156:157]
	s_add_i32 m0, s21, 0x1e000
	s_sext_i32_i16 s57, s0
	global_load_lds_dwordx4 v[2:3], off
	v_and_b32_e32 v2, 15, v0
	v_lshlrev_b32_e32 v3, 2, v0
	v_lshlrev_b32_e32 v4, 6, v0
	s_movk_i32 s0, 0x3c0
	v_lshl_or_b32 v1, s3, 6, v2
	v_lshl_or_b32 v2, v2, 6, v154
	v_and_b32_e32 v3, 32, v3
	v_and_or_b32 v4, v4, s0, v154
	v_bitop3_b32 v2, v2, s13, v3 bitop3:0xde
	v_bitop3_b32 v180, s14, v4, v3 bitop3:0xf6
	v_lshlrev_b32_e32 v3, 8, v0
	v_and_b32_e32 v3, 0x18000, v3
	v_lshlrev_b32_e32 v4, 11, v13
	v_or3_b32 v3, v11, v3, v4
	v_add_u32_e32 v164, v3, v12
	v_lshlrev_b32_e32 v3, 4, v10
	s_waitcnt vmcnt(6)
	v_and_b32_e32 v3, 0x38000, v3
	v_mov_b32_e32 v28, v161
	v_mov_b32_e32 v29, v161
	s_cmpk_lt_u32 s2, 0x100
	v_or3_b32 v3, v11, v3, v4
	v_mov_b32_e32 v26, v161
	v_mov_b32_e32 v27, v161
	v_mov_b64_e32 v[32:33], v[28:29]
	v_mov_b64_e32 v[36:37], v[28:29]
	v_mov_b64_e32 v[40:41], v[28:29]
	v_mov_b64_e32 v[44:45], v[28:29]
	v_mov_b64_e32 v[48:49], v[28:29]
	v_mov_b64_e32 v[52:53], v[28:29]
	v_mov_b64_e32 v[56:57], v[28:29]
	v_mov_b64_e32 v[60:61], v[28:29]
	v_mov_b64_e32 v[64:65], v[28:29]
	v_mov_b64_e32 v[68:69], v[28:29]
	v_mov_b64_e32 v[72:73], v[28:29]
	v_mov_b64_e32 v[76:77], v[28:29]
	v_mov_b64_e32 v[80:81], v[28:29]
	v_mov_b64_e32 v[84:85], v[28:29]
	v_mov_b64_e32 v[88:89], v[28:29]
	v_mov_b64_e32 v[92:93], v[28:29]
	v_mov_b64_e32 v[96:97], v[28:29]
	v_mov_b64_e32 v[100:101], v[28:29]
	v_mov_b64_e32 v[104:105], v[28:29]
	v_mov_b64_e32 v[108:109], v[28:29]
	v_mov_b64_e32 v[112:113], v[28:29]
	v_mov_b64_e32 v[116:117], v[28:29]
	v_mov_b64_e32 v[120:121], v[28:29]
	v_mov_b64_e32 v[124:125], v[28:29]
	v_mov_b64_e32 v[128:129], v[28:29]
	v_mov_b64_e32 v[132:133], v[28:29]
	v_mov_b64_e32 v[136:137], v[28:29]
	v_mov_b64_e32 v[140:141], v[28:29]
	v_mov_b64_e32 v[144:145], v[28:29]
	v_mov_b64_e32 v[148:149], v[28:29]
	v_mov_b64_e32 v[152:153], v[28:29]
	s_cselect_b64 s[10:11], -1, 0
	s_lshl_b32 s0, s12, 6
	v_mov_b32_e32 v155, v161
	s_ashr_i32 s45, s33, 31
	v_mov_b32_e32 v165, v161
	v_add_u32_e32 v166, v3, v12
	v_mov_b32_e32 v167, v161
	v_mov_b64_e32 v[168:169], 0xa00
	v_mov_b64_e32 v[170:171], 0x9ff
	s_add_i32 s46, 0, 0x10000
	s_add_i32 s47, 0, 0x14000
	v_add_u32_e32 v181, 0, v2
	v_mov_b32_e32 v182, 0x7b7b7b7b
	s_mov_b32 s48, 0x20000
	s_mov_b32 s49, 0x40000
	s_mov_b32 s52, 0x60000
	s_mov_b32 s53, 0x100000
	s_mov_b32 s54, 0x120000
	s_mov_b32 s55, 0x140000
	v_mov_b32_e32 v183, 0x41a947ae
	v_mov_b64_e32 v[30:31], v[26:27]
	v_mov_b64_e32 v[34:35], v[26:27]
	v_mov_b64_e32 v[38:39], v[26:27]
	v_mov_b64_e32 v[42:43], v[26:27]
	v_mov_b64_e32 v[46:47], v[26:27]
	v_mov_b64_e32 v[50:51], v[26:27]
	v_mov_b64_e32 v[54:55], v[26:27]
	v_mov_b64_e32 v[58:59], v[26:27]
	v_mov_b64_e32 v[62:63], v[26:27]
	v_mov_b64_e32 v[66:67], v[26:27]
	v_mov_b64_e32 v[70:71], v[26:27]
	v_mov_b64_e32 v[74:75], v[26:27]
	v_mov_b64_e32 v[78:79], v[26:27]
	v_mov_b64_e32 v[82:83], v[26:27]
	v_mov_b64_e32 v[86:87], v[26:27]
	v_mov_b64_e32 v[90:91], v[26:27]
	v_mov_b64_e32 v[94:95], v[26:27]
	v_mov_b64_e32 v[98:99], v[26:27]
	v_mov_b64_e32 v[102:103], v[26:27]
	v_mov_b64_e32 v[106:107], v[26:27]
	v_mov_b64_e32 v[110:111], v[26:27]
	v_mov_b64_e32 v[114:115], v[26:27]
	v_mov_b64_e32 v[118:119], v[26:27]
	v_mov_b64_e32 v[122:123], v[26:27]
	v_mov_b64_e32 v[126:127], v[26:27]
	v_mov_b64_e32 v[130:131], v[26:27]
	v_mov_b64_e32 v[134:135], v[26:27]
	v_mov_b64_e32 v[138:139], v[26:27]
	v_mov_b64_e32 v[142:143], v[26:27]
	v_mov_b64_e32 v[146:147], v[26:27]
	v_mov_b64_e32 v[150:151], v[26:27]
	s_mov_b32 s56, s1
	s_barrier
	s_branch .LBB0_736

.LBB0_739:
	v_add_u32_e32 v14, s46, v180
	v_add_u32_e32 v172, s47, v180
	ds_read_b128 v[2:5], v14
	ds_read_b128 v[6:9], v14 offset:1024
	ds_read_b128 v[10:13], v14 offset:2048
	ds_read_b128 v[14:17], v14 offset:3072
	ds_read_b128 v[18:21], v172
	ds_read_b128 v[22:25], v172 offset:1024
	ds_read_b128 v[184:187], v172 offset:2048
	ds_read_b128 v[188:191], v172 offset:3072
	s_add_u32 s24, s22, 0xfffc0080
	s_addc_u32 s25, s23, -1
	s_cmp_eq_u32 s62, 12
	s_cselect_b32 s27, s15, s25
	s_cselect_b32 s26, s58, s24
	s_cselect_b32 s25, s13, s61
	s_cselect_b32 s24, s59, s60
	v_lshl_add_u64 v[216:217], s[22:23], 0, v[164:165]
	s_add_i32 m0, s21, 0xc000
	ds_read_b128 v[172:175], v181
	ds_read_b128 v[176:179], v181 offset:1024
	ds_read_b128 v[192:195], v181 offset:2048
	ds_read_b128 v[196:199], v181 offset:3072
	ds_read_b128 v[200:203], v181 offset:4096
	ds_read_b128 v[204:207], v181 offset:5120
	ds_read_b128 v[208:211], v181 offset:6144
	ds_read_b128 v[212:215], v181 offset:7168
	global_load_lds_dwordx4 v[216:217], off
	v_lshl_add_u64 v[216:217], s[22:23], 0, v[166:167]
	s_add_i32 m0, s21, 0xe000
	s_nop 0
	global_load_lds_dwordx4 v[216:217], off
	s_waitcnt vmcnt(8)
	s_waitcnt lgkmcnt(0)
	s_cmp_lg_u32 s98, 0
	s_cbranch_scc1 .Lhb_p7_0
	s_barrier
.Lhb_p7_0:
	s_setprio 1
	s_waitcnt lgkmcnt(0)
	v_mfma_scale_f32_16x16x128_f8f6f4 v[150:153], v[2:9], v[172:179], v[150:153], v182, v182 op_sel_hi:[0,0,0]
	v_mfma_scale_f32_16x16x128_f8f6f4 v[146:149], v[10:17], v[172:179], v[146:149], v182, v182 op_sel_hi:[0,0,0]
	v_mfma_scale_f32_16x16x128_f8f6f4 v[142:145], v[2:9], v[192:199], v[142:145], v182, v182 op_sel_hi:[0,0,0]
	v_mfma_scale_f32_16x16x128_f8f6f4 v[138:141], v[10:17], v[192:199], v[138:141], v182, v182 op_sel_hi:[0,0,0]
	v_mfma_scale_f32_16x16x128_f8f6f4 v[134:137], v[2:9], v[200:207], v[134:137], v182, v182 op_sel_hi:[0,0,0]
	v_mfma_scale_f32_16x16x128_f8f6f4 v[130:133], v[10:17], v[200:207], v[130:133], v182, v182 op_sel_hi:[0,0,0]
	v_mfma_scale_f32_16x16x128_f8f6f4 v[126:129], v[2:9], v[208:215], v[126:129], v182, v182 op_sel_hi:[0,0,0]
	v_mfma_scale_f32_16x16x128_f8f6f4 v[122:125], v[10:17], v[208:215], v[122:125], v182, v182 op_sel_hi:[0,0,0]
	s_setprio 0
	s_setprio 1
	v_mfma_scale_f32_16x16x128_f8f6f4 v[118:121], v[18:25], v[172:179], v[118:121], v182, v182 op_sel_hi:[0,0,0]
	v_mfma_scale_f32_16x16x128_f8f6f4 v[114:117], v[184:191], v[172:179], v[114:117], v182, v182 op_sel_hi:[0,0,0]
	v_mfma_scale_f32_16x16x128_f8f6f4 v[110:113], v[18:25], v[192:199], v[110:113], v182, v182 op_sel_hi:[0,0,0]
	v_mfma_scale_f32_16x16x128_f8f6f4 v[106:109], v[184:191], v[192:199], v[106:109], v182, v182 op_sel_hi:[0,0,0]
	v_mfma_scale_f32_16x16x128_f8f6f4 v[102:105], v[18:25], v[200:207], v[102:105], v182, v182 op_sel_hi:[0,0,0]
	v_mfma_scale_f32_16x16x128_f8f6f4 v[98:101], v[184:191], v[200:207], v[98:101], v182, v182 op_sel_hi:[0,0,0]
	v_mfma_scale_f32_16x16x128_f8f6f4 v[94:97], v[18:25], v[208:215], v[94:97], v182, v182 op_sel_hi:[0,0,0]
	v_mfma_scale_f32_16x16x128_f8f6f4 v[90:93], v[184:191], v[208:215], v[90:93], v182, v182 op_sel_hi:[0,0,0]
	s_setprio 0
	s_cmp_lg_u32 s98, 1
	s_cbranch_scc1 .Lhb_p7_1
	s_barrier
.Lhb_p7_1:
	s_add_i32 s50, s46, s37
	v_lshl_add_u64 v[172:173], s[24:25], 0, v[160:161]
	s_mov_b32 m0, s50
	ds_read_b128 v[192:195], v181 offset:16384
	ds_read_b128 v[196:199], v181 offset:17408
	ds_read_b128 v[200:203], v181 offset:18432
	ds_read_b128 v[204:207], v181 offset:19456
	ds_read_b128 v[208:211], v181 offset:20480
	ds_read_b128 v[212:215], v181 offset:21504
	ds_read_b128 v[216:219], v181 offset:22528
	ds_read_b128 v[220:223], v181 offset:23552
	global_load_lds_dwordx4 v[172:173], off
	s_add_i32 m0, s50, 0x2000
	s_add_u32 s64, s24, 0x4000
	v_lshl_add_u64 v[174:175], s[24:25], 0, v[156:157]
	s_addc_u32 s65, s25, 0
	s_add_i32 s50, s47, s37
	global_load_lds_dwordx4 v[174:175], off
	v_lshl_add_u64 v[176:177], s[64:65], 0, v[160:161]
	s_mov_b32 m0, s50
	v_lshl_add_u64 v[178:179], s[26:27], 0, v[158:159]
	global_load_lds_dwordx4 v[176:177], off
	v_lshl_add_u64 v[176:177], s[64:65], 0, v[156:157]
	s_add_i32 m0, s50, 0x2000
	s_nop 0
	global_load_lds_dwordx4 v[176:177], off
	v_lshl_add_u64 v[176:177], s[26:27], 0, v[162:163]
	s_mov_b32 m0, s21
	s_nop 0
	global_load_lds_dwordx4 v[176:177], off
	s_mov_b32 m0, s40
	s_nop 0
	global_load_lds_dwordx4 v[178:179], off
	s_waitcnt vmcnt(8)
	s_waitcnt lgkmcnt(0)
	s_cmp_lg_u32 s98, 0
	s_cbranch_scc1 .Lhb_p7_2
	s_barrier
.Lhb_p7_2:
	s_setprio 1
	s_waitcnt lgkmcnt(0)
	v_mfma_scale_f32_16x16x128_f8f6f4 v[86:89], v[2:9], v[192:199], v[86:89], v182, v182 op_sel_hi:[0,0,0]
	v_mfma_scale_f32_16x16x128_f8f6f4 v[82:85], v[10:17], v[192:199], v[82:85], v182, v182 op_sel_hi:[0,0,0]
	v_mfma_scale_f32_16x16x128_f8f6f4 v[78:81], v[2:9], v[200:207], v[78:81], v182, v182 op_sel_hi:[0,0,0]
	v_mfma_scale_f32_16x16x128_f8f6f4 v[74:77], v[10:17], v[200:207], v[74:77], v182, v182 op_sel_hi:[0,0,0]
	v_mfma_scale_f32_16x16x128_f8f6f4 v[70:73], v[2:9], v[208:215], v[70:73], v182, v182 op_sel_hi:[0,0,0]
	v_mfma_scale_f32_16x16x128_f8f6f4 v[66:69], v[10:17], v[208:215], v[66:69], v182, v182 op_sel_hi:[0,0,0]
	v_mfma_scale_f32_16x16x128_f8f6f4 v[62:65], v[2:9], v[216:223], v[62:65], v182, v182 op_sel_hi:[0,0,0]
	v_mfma_scale_f32_16x16x128_f8f6f4 v[58:61], v[10:17], v[216:223], v[58:61], v182, v182 op_sel_hi:[0,0,0]
	s_setprio 0
	s_setprio 1
	v_mfma_scale_f32_16x16x128_f8f6f4 v[54:57], v[18:25], v[192:199], v[54:57], v182, v182 op_sel_hi:[0,0,0]
	v_mfma_scale_f32_16x16x128_f8f6f4 v[50:53], v[184:191], v[192:199], v[50:53], v182, v182 op_sel_hi:[0,0,0]
	v_mfma_scale_f32_16x16x128_f8f6f4 v[46:49], v[18:25], v[200:207], v[46:49], v182, v182 op_sel_hi:[0,0,0]
	v_mfma_scale_f32_16x16x128_f8f6f4 v[42:45], v[184:191], v[200:207], v[42:45], v182, v182 op_sel_hi:[0,0,0]
	v_mfma_scale_f32_16x16x128_f8f6f4 v[38:41], v[18:25], v[208:215], v[38:41], v182, v182 op_sel_hi:[0,0,0]
	v_mfma_scale_f32_16x16x128_f8f6f4 v[34:37], v[184:191], v[208:215], v[34:37], v182, v182 op_sel_hi:[0,0,0]
	v_mfma_scale_f32_16x16x128_f8f6f4 v[30:33], v[18:25], v[216:223], v[30:33], v182, v182 op_sel_hi:[0,0,0]
	v_mfma_scale_f32_16x16x128_f8f6f4 v[26:29], v[184:191], v[216:223], v[26:29], v182, v182 op_sel_hi:[0,0,0]
	s_setprio 0
	s_cmp_lg_u32 s98, 1
	s_cbranch_scc1 .Lhb_p7_3
	s_barrier
.Lhb_p7_3:
	s_add_i32 s63, 0, 0x18000
	s_add_i32 s50, 0, 0x1c000
	v_add_u32_e32 v2, s63, v180
	v_add_u32_e32 v22, s50, v180
	ds_read_b128 v[10:13], v2
	ds_read_b128 v[14:17], v2 offset:1024
	ds_read_b128 v[184:187], v2 offset:2048
	ds_read_b128 v[188:191], v2 offset:3072
	ds_read_b128 v[2:5], v22
	ds_read_b128 v[6:9], v22 offset:1024
	ds_read_b128 v[18:21], v22 offset:2048
	ds_read_b128 v[22:25], v22 offset:3072
	s_add_u32 s26, s26, 0x40000
	s_addc_u32 s27, s27, 0
	s_mov_b32 m0, s41
	v_lshl_add_u64 v[224:225], s[26:27], 0, v[162:163]
	ds_read_b128 v[192:195], v181 offset:32768
	ds_read_b128 v[196:199], v181 offset:33792
	ds_read_b128 v[200:203], v181 offset:34816
	ds_read_b128 v[204:207], v181 offset:35840
	ds_read_b128 v[208:211], v181 offset:36864
	ds_read_b128 v[212:215], v181 offset:37888
	ds_read_b128 v[216:219], v181 offset:38912
	ds_read_b128 v[220:223], v181 offset:39936
	global_load_lds_dwordx4 v[224:225], off
	v_lshl_add_u64 v[224:225], s[26:27], 0, v[158:159]
	s_mov_b32 m0, s42
	s_nop 0
	global_load_lds_dwordx4 v[224:225], off
	s_waitcnt vmcnt(8)
	s_waitcnt lgkmcnt(0)
	s_cmp_lg_u32 s98, 0
	s_cbranch_scc1 .Lhb_p7_4
	s_barrier
.Lhb_p7_4:
	s_setprio 1
	s_waitcnt lgkmcnt(0)
	v_mfma_scale_f32_16x16x128_f8f6f4 v[150:153], v[10:17], v[192:199], v[150:153], v182, v182 op_sel_hi:[0,0,0]
	v_mfma_scale_f32_16x16x128_f8f6f4 v[146:149], v[184:191], v[192:199], v[146:149], v182, v182 op_sel_hi:[0,0,0]
	v_mfma_scale_f32_16x16x128_f8f6f4 v[142:145], v[10:17], v[200:207], v[142:145], v182, v182 op_sel_hi:[0,0,0]
	v_mfma_scale_f32_16x16x128_f8f6f4 v[138:141], v[184:191], v[200:207], v[138:141], v182, v182 op_sel_hi:[0,0,0]
	v_mfma_scale_f32_16x16x128_f8f6f4 v[134:137], v[10:17], v[208:215], v[134:137], v182, v182 op_sel_hi:[0,0,0]
	v_mfma_scale_f32_16x16x128_f8f6f4 v[130:133], v[184:191], v[208:215], v[130:133], v182, v182 op_sel_hi:[0,0,0]
	v_mfma_scale_f32_16x16x128_f8f6f4 v[126:129], v[10:17], v[216:223], v[126:129], v182, v182 op_sel_hi:[0,0,0]
	v_mfma_scale_f32_16x16x128_f8f6f4 v[122:125], v[184:191], v[216:223], v[122:125], v182, v182 op_sel_hi:[0,0,0]
	s_setprio 0
	s_setprio 1
	v_mfma_scale_f32_16x16x128_f8f6f4 v[118:121], v[2:9], v[192:199], v[118:121], v182, v182 op_sel_hi:[0,0,0]
	v_mfma_scale_f32_16x16x128_f8f6f4 v[114:117], v[18:25], v[192:199], v[114:117], v182, v182 op_sel_hi:[0,0,0]
	v_mfma_scale_f32_16x16x128_f8f6f4 v[110:113], v[2:9], v[200:207], v[110:113], v182, v182 op_sel_hi:[0,0,0]
	v_mfma_scale_f32_16x16x128_f8f6f4 v[106:109], v[18:25], v[200:207], v[106:109], v182, v182 op_sel_hi:[0,0,0]
	v_mfma_scale_f32_16x16x128_f8f6f4 v[102:105], v[2:9], v[208:215], v[102:105], v182, v182 op_sel_hi:[0,0,0]
	v_mfma_scale_f32_16x16x128_f8f6f4 v[98:101], v[18:25], v[208:215], v[98:101], v182, v182 op_sel_hi:[0,0,0]
	v_mfma_scale_f32_16x16x128_f8f6f4 v[94:97], v[2:9], v[216:223], v[94:97], v182, v182 op_sel_hi:[0,0,0]
	v_mfma_scale_f32_16x16x128_f8f6f4 v[90:93], v[18:25], v[216:223], v[90:93], v182, v182 op_sel_hi:[0,0,0]
	s_setprio 0
	s_cmp_lg_u32 s98, 1
	s_cbranch_scc1 .Lhb_p7_5
	s_barrier
.Lhb_p7_5:
	s_add_i32 s26, s63, s37
	v_lshl_add_u64 v[172:173], v[172:173], 0, s[8:9]
	s_mov_b32 m0, s26
	ds_read_b128 v[192:195], v181 offset:49152
	ds_read_b128 v[196:199], v181 offset:50176
	ds_read_b128 v[200:203], v181 offset:51200
	ds_read_b128 v[204:207], v181 offset:52224
	ds_read_b128 v[208:211], v181 offset:53248
	ds_read_b128 v[212:215], v181 offset:54272
	ds_read_b128 v[216:219], v181 offset:55296
	ds_read_b128 v[220:223], v181 offset:56320
	global_load_lds_dwordx4 v[172:173], off
	s_add_i32 m0, s26, 0x2000
	s_add_u32 s24, s24, 0x4080
	v_lshl_add_u64 v[172:173], v[174:175], 0, s[8:9]
	s_addc_u32 s25, s25, 0
	s_add_i32 s26, s50, s37
	global_load_lds_dwordx4 v[172:173], off
	v_lshl_add_u64 v[172:173], s[24:25], 0, v[160:161]
	s_mov_b32 m0, s26
	s_nop 0
	global_load_lds_dwordx4 v[172:173], off
	v_lshl_add_u64 v[172:173], s[24:25], 0, v[156:157]
	s_add_i32 m0, s26, 0x2000
	s_nop 0
	global_load_lds_dwordx4 v[172:173], off
	v_lshl_add_u64 v[172:173], v[176:177], 0, s[8:9]
	s_mov_b32 m0, s43
	s_nop 0
	global_load_lds_dwordx4 v[172:173], off
	v_lshl_add_u64 v[172:173], v[178:179], 0, s[8:9]
	s_mov_b32 m0, s44
	s_nop 0
	global_load_lds_dwordx4 v[172:173], off
	s_waitcnt vmcnt(8)
	s_waitcnt lgkmcnt(0)
	s_cmp_lg_u32 s98, 0
	s_cbranch_scc1 .Lhb_p7_6
	s_barrier
.Lhb_p7_6:
	s_setprio 1
	s_waitcnt lgkmcnt(0)
	v_mfma_scale_f32_16x16x128_f8f6f4 v[86:89], v[10:17], v[192:199], v[86:89], v182, v182 op_sel_hi:[0,0,0]
	v_mfma_scale_f32_16x16x128_f8f6f4 v[82:85], v[184:191], v[192:199], v[82:85], v182, v182 op_sel_hi:[0,0,0]
	v_mfma_scale_f32_16x16x128_f8f6f4 v[78:81], v[10:17], v[200:207], v[78:81], v182, v182 op_sel_hi:[0,0,0]
	v_mfma_scale_f32_16x16x128_f8f6f4 v[74:77], v[184:191], v[200:207], v[74:77], v182, v182 op_sel_hi:[0,0,0]
	v_mfma_scale_f32_16x16x128_f8f6f4 v[70:73], v[10:17], v[208:215], v[70:73], v182, v182 op_sel_hi:[0,0,0]
	v_mfma_scale_f32_16x16x128_f8f6f4 v[66:69], v[184:191], v[208:215], v[66:69], v182, v182 op_sel_hi:[0,0,0]
	v_mfma_scale_f32_16x16x128_f8f6f4 v[62:65], v[10:17], v[216:223], v[62:65], v182, v182 op_sel_hi:[0,0,0]
	v_mfma_scale_f32_16x16x128_f8f6f4 v[58:61], v[184:191], v[216:223], v[58:61], v182, v182 op_sel_hi:[0,0,0]
	s_setprio 0
	s_setprio 1
	v_mfma_scale_f32_16x16x128_f8f6f4 v[54:57], v[2:9], v[192:199], v[54:57], v182, v182 op_sel_hi:[0,0,0]
	v_mfma_scale_f32_16x16x128_f8f6f4 v[50:53], v[18:25], v[192:199], v[50:53], v182, v182 op_sel_hi:[0,0,0]
	v_mfma_scale_f32_16x16x128_f8f6f4 v[46:49], v[2:9], v[200:207], v[46:49], v182, v182 op_sel_hi:[0,0,0]
	v_mfma_scale_f32_16x16x128_f8f6f4 v[42:45], v[18:25], v[200:207], v[42:45], v182, v182 op_sel_hi:[0,0,0]
	v_mfma_scale_f32_16x16x128_f8f6f4 v[38:41], v[2:9], v[208:215], v[38:41], v182, v182 op_sel_hi:[0,0,0]
	v_mfma_scale_f32_16x16x128_f8f6f4 v[34:37], v[18:25], v[208:215], v[34:37], v182, v182 op_sel_hi:[0,0,0]
	v_mfma_scale_f32_16x16x128_f8f6f4 v[30:33], v[2:9], v[216:223], v[30:33], v182, v182 op_sel_hi:[0,0,0]
	v_mfma_scale_f32_16x16x128_f8f6f4 v[26:29], v[18:25], v[216:223], v[26:29], v182, v182 op_sel_hi:[0,0,0]
	s_setprio 0
	s_cmp_lg_u32 s98, 1
	s_cbranch_scc1 .Lhb_p7_7
	s_barrier
.Lhb_p7_7:
	s_add_i32 s62, s62, 2
	s_add_u32 s22, s22, 0x100
	s_addc_u32 s23, s23, 0
	s_add_u32 s60, s60, 0x100
	s_addc_u32 s61, s61, 0
	s_cmp_gt_u32 s62, 13
	s_cbranch_scc0 .LBB0_739
	s_and_b64 vcc, exec, s[10:11]
	s_cbranch_vccz .LBB0_742
.LBB0_742:
	v_med3_f32 v4, v150, 0, v183
	v_med3_f32 v6, v146, 0, v183
	v_med3_f32 v5, v151, 0, v183
	v_med3_f32 v7, v147, 0, v183
	v_pk_mul_f32 v[12:13], v[4:5], v[4:5]
	v_pk_mul_f32 v[6:7], v[6:7], v[6:7]
	v_mov_b32_e32 v4, 0
	v_mov_b32_e32 v5, 0
	v_cvt_pk_fp8_f32 v4, v12, v13
	v_cvt_pk_fp8_f32 v5, v6, v7
	v_med3_f32 v8, v152, 0, v183
	v_med3_f32 v10, v148, 0, v183
	v_med3_f32 v9, v153, 0, v183
	v_med3_f32 v11, v149, 0, v183
	v_pk_mul_f32 v[6:7], v[8:9], v[8:9]
	v_pk_mul_f32 v[8:9], v[10:11], v[10:11]
	v_cvt_pk_fp8_f32 v4, v6, v7 op_sel:[0,0,1]
	v_cvt_pk_fp8_f32 v5, v8, v9 op_sel:[0,0,1]
	v_med3_f32 v6, v118, 0, v183
	v_med3_f32 v8, v114, 0, v183
	v_med3_f32 v7, v119, 0, v183
	v_med3_f32 v9, v115, 0, v183
	v_pk_mul_f32 v[14:15], v[6:7], v[6:7]
	v_pk_mul_f32 v[8:9], v[8:9], v[8:9]
	v_mov_b32_e32 v6, 0
	v_mov_b32_e32 v7, 0
	v_cvt_pk_fp8_f32 v6, v14, v15
	v_cvt_pk_fp8_f32 v7, v8, v9
	v_lshl_add_u32 v2, s20, 8, v1
	v_ashrrev_i32_e32 v3, 31, v2
	v_med3_f32 v10, v120, 0, v183
	v_med3_f32 v12, v116, 0, v183
	v_med3_f32 v11, v121, 0, v183
	v_med3_f32 v13, v117, 0, v183
	v_lshlrev_b64 v[2:3], 13, v[2:3]
	s_lshl_b32 s22, s57, 8
	v_pk_mul_f32 v[8:9], v[10:11], v[10:11]
	v_pk_mul_f32 v[10:11], v[12:13], v[12:13]
	v_lshl_add_u64 v[2:3], s[6:7], 0, v[2:3]
	s_ashr_i32 s23, s22, 31
	v_cvt_pk_fp8_f32 v6, v8, v9 op_sel:[0,0,1]
	v_cvt_pk_fp8_f32 v7, v10, v11 op_sel:[0,0,1]
	v_lshl_add_u64 v[2:3], v[2:3], 0, s[22:23]
	v_lshl_add_u64 v[2:3], v[2:3], 0, s[0:1]
	v_lshl_add_u64 v[2:3], v[2:3], 0, v[154:155]
	s_nop 15
	s_nop 15
	global_store_dwordx4 v[2:3], v[4:7], off
	v_med3_f32 v8, v144, 0, v183
	v_med3_f32 v10, v140, 0, v183
	v_med3_f32 v4, v142, 0, v183
	v_med3_f32 v6, v138, 0, v183
	v_med3_f32 v5, v143, 0, v183
	v_med3_f32 v7, v139, 0, v183
	v_pk_mul_f32 v[12:13], v[4:5], v[4:5]
	v_pk_mul_f32 v[6:7], v[6:7], v[6:7]
	v_mov_b32_e32 v4, 0
	v_mov_b32_e32 v5, 0
	v_cvt_pk_fp8_f32 v4, v12, v13
	v_cvt_pk_fp8_f32 v5, v6, v7
	v_med3_f32 v9, v145, 0, v183
	v_med3_f32 v11, v141, 0, v183
	v_pk_mul_f32 v[6:7], v[8:9], v[8:9]
	v_pk_mul_f32 v[8:9], v[10:11], v[10:11]
	v_cvt_pk_fp8_f32 v4, v6, v7 op_sel:[0,0,1]
	v_cvt_pk_fp8_f32 v5, v8, v9 op_sel:[0,0,1]
	v_med3_f32 v6, v110, 0, v183
	v_med3_f32 v8, v106, 0, v183
	v_med3_f32 v7, v111, 0, v183
	v_med3_f32 v9, v107, 0, v183
	v_pk_mul_f32 v[14:15], v[6:7], v[6:7]
	v_pk_mul_f32 v[8:9], v[8:9], v[8:9]
	v_mov_b32_e32 v6, 0
	v_mov_b32_e32 v7, 0
	v_cvt_pk_fp8_f32 v6, v14, v15
	v_cvt_pk_fp8_f32 v7, v8, v9
	v_med3_f32 v10, v112, 0, v183
	v_med3_f32 v12, v108, 0, v183
	v_med3_f32 v11, v113, 0, v183
	v_med3_f32 v13, v109, 0, v183
	v_pk_mul_f32 v[8:9], v[10:11], v[10:11]
	v_pk_mul_f32 v[10:11], v[12:13], v[12:13]
	v_cvt_pk_fp8_f32 v6, v8, v9 op_sel:[0,0,1]
	v_cvt_pk_fp8_f32 v7, v10, v11 op_sel:[0,0,1]
	v_add_co_u32_e32 v8, vcc, s48, v2
	v_med3_f32 v10, v132, 0, v183
	s_nop 0
	v_addc_co_u32_e32 v9, vcc, 0, v3, vcc
	global_store_dwordx4 v[8:9], v[4:7], off
	v_med3_f32 v8, v136, 0, v183
	v_med3_f32 v9, v137, 0, v183
	v_med3_f32 v4, v134, 0, v183
	v_med3_f32 v6, v130, 0, v183
	v_med3_f32 v5, v135, 0, v183
	v_med3_f32 v7, v131, 0, v183
	v_pk_mul_f32 v[12:13], v[4:5], v[4:5]
	v_pk_mul_f32 v[6:7], v[6:7], v[6:7]
	v_mov_b32_e32 v4, 0
	v_mov_b32_e32 v5, 0
	v_cvt_pk_fp8_f32 v4, v12, v13
	v_cvt_pk_fp8_f32 v5, v6, v7
	v_med3_f32 v11, v133, 0, v183
	v_pk_mul_f32 v[6:7], v[8:9], v[8:9]
	v_pk_mul_f32 v[8:9], v[10:11], v[10:11]
	v_cvt_pk_fp8_f32 v4, v6, v7 op_sel:[0,0,1]
	v_cvt_pk_fp8_f32 v5, v8, v9 op_sel:[0,0,1]
	v_med3_f32 v6, v102, 0, v183
	v_med3_f32 v8, v98, 0, v183
	v_med3_f32 v7, v103, 0, v183
	v_med3_f32 v9, v99, 0, v183
	v_pk_mul_f32 v[14:15], v[6:7], v[6:7]
	v_pk_mul_f32 v[8:9], v[8:9], v[8:9]
	v_mov_b32_e32 v6, 0
	v_mov_b32_e32 v7, 0
	v_cvt_pk_fp8_f32 v6, v14, v15
	v_cvt_pk_fp8_f32 v7, v8, v9
	v_med3_f32 v10, v104, 0, v183
	v_med3_f32 v12, v100, 0, v183
	v_med3_f32 v11, v105, 0, v183
	v_med3_f32 v13, v101, 0, v183
	v_pk_mul_f32 v[8:9], v[10:11], v[10:11]
	v_pk_mul_f32 v[10:11], v[12:13], v[12:13]
	v_cvt_pk_fp8_f32 v6, v8, v9 op_sel:[0,0,1]
	v_cvt_pk_fp8_f32 v7, v10, v11 op_sel:[0,0,1]
	v_add_co_u32_e32 v8, vcc, s49, v2
	v_med3_f32 v10, v124, 0, v183
	s_nop 0
	v_addc_co_u32_e32 v9, vcc, 0, v3, vcc
	global_store_dwordx4 v[8:9], v[4:7], off
	v_med3_f32 v8, v128, 0, v183
	v_med3_f32 v9, v129, 0, v183
	v_med3_f32 v4, v126, 0, v183
	v_med3_f32 v6, v122, 0, v183
	v_med3_f32 v5, v127, 0, v183
	v_med3_f32 v7, v123, 0, v183
	v_pk_mul_f32 v[12:13], v[4:5], v[4:5]
	v_pk_mul_f32 v[6:7], v[6:7], v[6:7]
	v_mov_b32_e32 v4, 0
	v_mov_b32_e32 v5, 0
	v_cvt_pk_fp8_f32 v4, v12, v13
	v_cvt_pk_fp8_f32 v5, v6, v7
	v_med3_f32 v11, v125, 0, v183
	v_pk_mul_f32 v[6:7], v[8:9], v[8:9]
	v_pk_mul_f32 v[8:9], v[10:11], v[10:11]
	v_cvt_pk_fp8_f32 v4, v6, v7 op_sel:[0,0,1]
	v_cvt_pk_fp8_f32 v5, v8, v9 op_sel:[0,0,1]
	v_med3_f32 v6, v94, 0, v183
	v_med3_f32 v8, v90, 0, v183
	v_med3_f32 v7, v95, 0, v183
	v_med3_f32 v9, v91, 0, v183
	v_pk_mul_f32 v[14:15], v[6:7], v[6:7]
	v_pk_mul_f32 v[8:9], v[8:9], v[8:9]
	v_mov_b32_e32 v6, 0
	v_mov_b32_e32 v7, 0
	v_cvt_pk_fp8_f32 v6, v14, v15
	v_cvt_pk_fp8_f32 v7, v8, v9
	v_med3_f32 v10, v96, 0, v183
	v_med3_f32 v12, v92, 0, v183
	v_med3_f32 v11, v97, 0, v183
	v_med3_f32 v13, v93, 0, v183
	v_pk_mul_f32 v[8:9], v[10:11], v[10:11]
	v_pk_mul_f32 v[10:11], v[12:13], v[12:13]
	v_cvt_pk_fp8_f32 v6, v8, v9 op_sel:[0,0,1]
	v_cvt_pk_fp8_f32 v7, v10, v11 op_sel:[0,0,1]
	v_add_co_u32_e32 v8, vcc, s52, v2
	v_med3_f32 v10, v84, 0, v183
	s_nop 0
	v_addc_co_u32_e32 v9, vcc, 0, v3, vcc
	global_store_dwordx4 v[8:9], v[4:7], off
	v_med3_f32 v8, v88, 0, v183
	v_med3_f32 v9, v89, 0, v183
	v_med3_f32 v4, v86, 0, v183
	v_med3_f32 v6, v82, 0, v183
	v_med3_f32 v5, v87, 0, v183
	v_med3_f32 v7, v83, 0, v183
	v_pk_mul_f32 v[12:13], v[4:5], v[4:5]
	v_pk_mul_f32 v[6:7], v[6:7], v[6:7]
	v_mov_b32_e32 v4, 0
	v_mov_b32_e32 v5, 0
	v_cvt_pk_fp8_f32 v4, v12, v13
	v_cvt_pk_fp8_f32 v5, v6, v7
	v_med3_f32 v11, v85, 0, v183
	v_pk_mul_f32 v[6:7], v[8:9], v[8:9]
	v_pk_mul_f32 v[8:9], v[10:11], v[10:11]
	v_cvt_pk_fp8_f32 v4, v6, v7 op_sel:[0,0,1]
	v_cvt_pk_fp8_f32 v5, v8, v9 op_sel:[0,0,1]
	v_med3_f32 v6, v54, 0, v183
	v_med3_f32 v8, v50, 0, v183
	v_med3_f32 v7, v55, 0, v183
	v_med3_f32 v9, v51, 0, v183
	v_pk_mul_f32 v[14:15], v[6:7], v[6:7]
	v_pk_mul_f32 v[8:9], v[8:9], v[8:9]
	v_mov_b32_e32 v6, 0
	v_mov_b32_e32 v7, 0
	v_cvt_pk_fp8_f32 v6, v14, v15
	v_cvt_pk_fp8_f32 v7, v8, v9
	v_med3_f32 v10, v56, 0, v183
	v_med3_f32 v12, v52, 0, v183
	v_med3_f32 v11, v57, 0, v183
	v_med3_f32 v13, v53, 0, v183
	v_pk_mul_f32 v[8:9], v[10:11], v[10:11]
	v_pk_mul_f32 v[10:11], v[12:13], v[12:13]
	v_cvt_pk_fp8_f32 v6, v8, v9 op_sel:[0,0,1]
	v_cvt_pk_fp8_f32 v7, v10, v11 op_sel:[0,0,1]
	v_add_co_u32_e32 v8, vcc, s53, v2
	v_med3_f32 v10, v76, 0, v183
	s_nop 0
	v_addc_co_u32_e32 v9, vcc, 0, v3, vcc
	global_store_dwordx4 v[8:9], v[4:7], off
	v_med3_f32 v8, v80, 0, v183
	v_med3_f32 v9, v81, 0, v183
	v_med3_f32 v4, v78, 0, v183
	v_med3_f32 v6, v74, 0, v183
	v_med3_f32 v5, v79, 0, v183
	v_med3_f32 v7, v75, 0, v183
	v_pk_mul_f32 v[12:13], v[4:5], v[4:5]
	v_pk_mul_f32 v[6:7], v[6:7], v[6:7]
	v_mov_b32_e32 v4, 0
	v_mov_b32_e32 v5, 0
	v_cvt_pk_fp8_f32 v4, v12, v13
	v_cvt_pk_fp8_f32 v5, v6, v7
	v_med3_f32 v11, v77, 0, v183
	v_pk_mul_f32 v[6:7], v[8:9], v[8:9]
	v_pk_mul_f32 v[8:9], v[10:11], v[10:11]
	v_cvt_pk_fp8_f32 v4, v6, v7 op_sel:[0,0,1]
	v_cvt_pk_fp8_f32 v5, v8, v9 op_sel:[0,0,1]
	v_med3_f32 v6, v46, 0, v183
	v_med3_f32 v8, v42, 0, v183
	v_med3_f32 v7, v47, 0, v183
	v_med3_f32 v9, v43, 0, v183
	v_pk_mul_f32 v[14:15], v[6:7], v[6:7]
	v_pk_mul_f32 v[8:9], v[8:9], v[8:9]
	v_mov_b32_e32 v6, 0
	v_mov_b32_e32 v7, 0
	v_cvt_pk_fp8_f32 v6, v14, v15
	v_cvt_pk_fp8_f32 v7, v8, v9
	v_med3_f32 v10, v48, 0, v183
	v_med3_f32 v12, v44, 0, v183
	v_med3_f32 v11, v49, 0, v183
	v_med3_f32 v13, v45, 0, v183
	v_pk_mul_f32 v[8:9], v[10:11], v[10:11]
	v_pk_mul_f32 v[10:11], v[12:13], v[12:13]
	v_cvt_pk_fp8_f32 v6, v8, v9 op_sel:[0,0,1]
	v_cvt_pk_fp8_f32 v7, v10, v11 op_sel:[0,0,1]
	v_add_co_u32_e32 v8, vcc, s54, v2
	v_med3_f32 v10, v68, 0, v183
	s_nop 0
	v_addc_co_u32_e32 v9, vcc, 0, v3, vcc
	global_store_dwordx4 v[8:9], v[4:7], off
	v_med3_f32 v8, v72, 0, v183
	v_med3_f32 v9, v73, 0, v183
	v_med3_f32 v4, v70, 0, v183
	v_med3_f32 v6, v66, 0, v183
	v_med3_f32 v5, v71, 0, v183
	v_med3_f32 v7, v67, 0, v183
	v_pk_mul_f32 v[12:13], v[4:5], v[4:5]
	v_pk_mul_f32 v[6:7], v[6:7], v[6:7]
	v_mov_b32_e32 v4, 0
	v_mov_b32_e32 v5, 0
	v_cvt_pk_fp8_f32 v4, v12, v13
	v_cvt_pk_fp8_f32 v5, v6, v7
	v_med3_f32 v11, v69, 0, v183
	v_pk_mul_f32 v[6:7], v[8:9], v[8:9]
	v_pk_mul_f32 v[8:9], v[10:11], v[10:11]
	v_cvt_pk_fp8_f32 v4, v6, v7 op_sel:[0,0,1]
	v_cvt_pk_fp8_f32 v5, v8, v9 op_sel:[0,0,1]
	v_med3_f32 v6, v38, 0, v183
	v_med3_f32 v8, v34, 0, v183
	v_med3_f32 v7, v39, 0, v183
	v_med3_f32 v9, v35, 0, v183
	v_pk_mul_f32 v[14:15], v[6:7], v[6:7]
	v_pk_mul_f32 v[8:9], v[8:9], v[8:9]
	v_mov_b32_e32 v6, 0
	v_mov_b32_e32 v7, 0
	v_cvt_pk_fp8_f32 v6, v14, v15
	v_cvt_pk_fp8_f32 v7, v8, v9
	v_med3_f32 v10, v40, 0, v183
	v_med3_f32 v12, v36, 0, v183
	v_med3_f32 v11, v41, 0, v183
	v_med3_f32 v13, v37, 0, v183
	v_pk_mul_f32 v[8:9], v[10:11], v[10:11]
	v_pk_mul_f32 v[10:11], v[12:13], v[12:13]
	v_cvt_pk_fp8_f32 v6, v8, v9 op_sel:[0,0,1]
	v_cvt_pk_fp8_f32 v7, v10, v11 op_sel:[0,0,1]
	v_add_co_u32_e32 v8, vcc, s55, v2
	v_med3_f32 v10, v60, 0, v183
	s_nop 0
	v_addc_co_u32_e32 v9, vcc, 0, v3, vcc
	global_store_dwordx4 v[8:9], v[4:7], off
	v_med3_f32 v8, v64, 0, v183
	v_med3_f32 v9, v65, 0, v183
	v_med3_f32 v4, v62, 0, v183
	v_med3_f32 v6, v58, 0, v183
	v_med3_f32 v5, v63, 0, v183
	v_med3_f32 v7, v59, 0, v183
	v_pk_mul_f32 v[12:13], v[4:5], v[4:5]
	v_pk_mul_f32 v[6:7], v[6:7], v[6:7]
	v_mov_b32_e32 v4, 0
	v_mov_b32_e32 v5, 0
	v_cvt_pk_fp8_f32 v4, v12, v13
	v_cvt_pk_fp8_f32 v5, v6, v7
	v_med3_f32 v11, v61, 0, v183
	v_pk_mul_f32 v[6:7], v[8:9], v[8:9]
	v_pk_mul_f32 v[8:9], v[10:11], v[10:11]
	v_cvt_pk_fp8_f32 v4, v6, v7 op_sel:[0,0,1]
	v_cvt_pk_fp8_f32 v5, v8, v9 op_sel:[0,0,1]
	v_med3_f32 v6, v30, 0, v183
	v_med3_f32 v8, v26, 0, v183
	v_med3_f32 v7, v31, 0, v183
	v_med3_f32 v9, v27, 0, v183
	v_pk_mul_f32 v[14:15], v[6:7], v[6:7]
	v_pk_mul_f32 v[8:9], v[8:9], v[8:9]
	v_mov_b32_e32 v6, 0
	v_mov_b32_e32 v7, 0
	v_cvt_pk_fp8_f32 v6, v14, v15
	v_cvt_pk_fp8_f32 v7, v8, v9
	v_med3_f32 v10, v32, 0, v183
	v_med3_f32 v12, v28, 0, v183
	v_med3_f32 v11, v33, 0, v183
	v_med3_f32 v13, v29, 0, v183
	v_pk_mul_f32 v[8:9], v[10:11], v[10:11]
	v_pk_mul_f32 v[10:11], v[12:13], v[12:13]
	v_cvt_pk_fp8_f32 v6, v8, v9 op_sel:[0,0,1]
	v_cvt_pk_fp8_f32 v7, v10, v11 op_sel:[0,0,1]
	v_add_co_u32_e32 v2, vcc, 0x160000, v2
	s_nop 1
	v_addc_co_u32_e32 v3, vcc, 0, v3, vcc
	s_andn2_b64 vcc, exec, s[2:3]
	s_mov_b64 s[2:3], -1
	global_store_dwordx4 v[2:3], v[4:7], off
	s_cbranch_vccnz .LBB0_735
	s_andn2_b64 vcc, exec, s[4:5]
	s_cbranch_vccnz .LBB0_734
	s_branch .LBB0_734

	.amdhsa_kernel _Z9hymba_fwd4Args
		.amdhsa_group_segment_fixed_size 0
		.amdhsa_private_segment_fixed_size 0
		.amdhsa_kernarg_size 432
		.amdhsa_user_sgpr_count 2
		.amdhsa_user_sgpr_dispatch_ptr 0
		.amdhsa_user_sgpr_queue_ptr 0
		.amdhsa_user_sgpr_kernarg_segment_ptr 1
		.amdhsa_user_sgpr_dispatch_id 0
		.amdhsa_user_sgpr_kernarg_preload_length 0
		.amdhsa_user_sgpr_kernarg_preload_offset 0
		.amdhsa_user_sgpr_private_segment_size 0
		.amdhsa_uses_dynamic_stack 0
		.amdhsa_enable_private_segment 0
		.amdhsa_system_sgpr_workgroup_id_x 1
		.amdhsa_system_sgpr_workgroup_id_y 0
		.amdhsa_system_sgpr_workgroup_id_z 0
		.amdhsa_system_sgpr_workgroup_info 0
		.amdhsa_system_vgpr_workitem_id 0
		.amdhsa_next_free_vgpr 255
		.amdhsa_next_free_sgpr 102
		.amdhsa_accum_offset 256
		.amdhsa_reserve_vcc 1
		.amdhsa_float_round_mode_32 0
		.amdhsa_float_round_mode_16_64 0
		.amdhsa_float_denorm_mode_32 3
		.amdhsa_float_denorm_mode_16_64 3
		.amdhsa_dx10_clamp 1
		.amdhsa_ieee_mode 1
		.amdhsa_fp16_overflow 0
		.amdhsa_tg_split 0
		.amdhsa_exception_fp_ieee_invalid_op 0
		.amdhsa_exception_fp_denorm_src 0
		.amdhsa_exception_fp_ieee_div_zero 0
		.amdhsa_exception_fp_ieee_overflow 0
		.amdhsa_exception_fp_ieee_underflow 0
		.amdhsa_exception_fp_ieee_inexact 0
		.amdhsa_exception_int_div_zero 0
	.end_amdhsa_kernel

amdhsa.kernels:
  - .agpr_count:     0
    .args:
      - .offset:         0
        .size:           176
        .value_kind:     by_value
      - .offset:         176
        .size:           4
        .value_kind:     hidden_block_count_x
      - .offset:         180
        .size:           4
        .value_kind:     hidden_block_count_y
      - .offset:         184
        .size:           4
        .value_kind:     hidden_block_count_z
      - .offset:         188
        .size:           2
        .value_kind:     hidden_group_size_x
      - .offset:         190
        .size:           2
        .value_kind:     hidden_group_size_y
      - .offset:         192
        .size:           2
        .value_kind:     hidden_group_size_z
      - .offset:         194
        .size:           2
        .value_kind:     hidden_remainder_x
      - .offset:         196
        .size:           2
        .value_kind:     hidden_remainder_y
      - .offset:         198
        .size:           2
        .value_kind:     hidden_remainder_z
      - .offset:         216
        .size:           8
        .value_kind:     hidden_global_offset_x
      - .offset:         224
        .size:           8
        .value_kind:     hidden_global_offset_y
      - .offset:         232
        .size:           8
        .value_kind:     hidden_global_offset_z
      - .offset:         240
        .size:           2
        .value_kind:     hidden_grid_dims
      - .offset:         296
        .size:           4
        .value_kind:     hidden_dynamic_lds_size
    .group_segment_fixed_size: 0
    .kernarg_segment_align: 8
    .kernarg_segment_size: 432
    .language:       OpenCL C
    .language_version:
      - 2
      - 0
    .max_flat_workgroup_size: 512
    .name:           _Z9hymba_fwd4Args
    .private_segment_fixed_size: 0
    .sgpr_count:     108
    .sgpr_spill_count: 29
    .symbol:         _Z9hymba_fwd4Args.kd
    .uniform_work_group_size: 1
    .uses_dynamic_stack: false
    .vgpr_count:     255
    .vgpr_spill_count: 0
    .wavefront_size: 64
